# V4 with the attention-phase static s_setprio 1 given to waves 0-3 instead of waves 4-7 (A/B)
# speedup vs baseline: 1.0039x; 1.0002x over previous
; #define OPAQUE_TID() int tid = MYTID(); asm volatile("" : "+v"(tid)); const int lane = tid & 63, wave = __builtin_amdgcn_readfirstlane(tid >> 6); (void)lane; (void)wave
; __global__ void __launch_bounds__(NTHREADS, 2) fwd_kernel(Args a) {
;     ...
;     if (IN(4)) { OPAQUE_TID();
;         if (wave >= 4) __builtin_amdgcn_s_setprio(1);
;         for (int U = vcu; U < 256; U += G) { int tu = tid; asm volatile("" : "+v"(tu)); compress_unit(U, a, lds, tu, wave, tu & 63); }
.LBB0_742:
	s_cmp_lt_i32 s42, 5
	s_cselect_b64 s[0:1], -1, 0
	s_and_b64 s[0:1], s[0:1], s[2:3]
	v_writelane_b32 v248, s0, 3
	s_andn2_b64 vcc, exec, s[0:1]
	s_nop 0
	v_writelane_b32 v248, s1, 4
	s_cbranch_vccnz .LBB0_990
	v_mbcnt_hi_u32_b32 v0, -1, v230
	v_readlane_b32 s0, v248, 0
	s_nop 1
	v_add_u32_e32 v214, s0, v0
	v_mov_b32_e32 v215, v214
	s_nop 0
	v_readfirstlane_b32 s1, v215
	s_ashr_i32 s0, s1, 6
	s_cmp_lt_i32 s0, 4
	s_cbranch_scc0 .LBB0_745
	s_setprio 1
